# attention near tiles: pre-clamped extended LDS bias table read with ds_read2_b32 immediate offsets (no per-element clamp VALU)
# speedup vs baseline: 1.0068x; 1.0068x over previous
.LBB0_596:
	s_bfe_u32 s2, s89, 0x30005
	v_mov_b32_e32 v141, v210
	s_movk_i32 s0, 0x1c0
	s_mul_i32 s6, s2, 0x104
	v_readfirstlane_b32 s4, v141
	v_cmp_gt_i32_e32 vcc, s0, v141
	s_and_saveexec_b64 s[0:1], vcc
	s_cbranch_execz .LBB0_598
	v_lshl_add_u32 v0, v141, 2, 0
	v_add_u32_e32 v2, 0x20000, v0
	v_add_u32_e32 v0, 0xffffffa0, v141
	v_max_i32_e32 v0, 0, v0
	v_min_i32_e32 v0, 0x100, v0
	v_add_u32_e32 v0, s6, v0
	v_readlane_b32 s8, v255, 22
	v_ashrrev_i32_e32 v1, 31, v0
	v_readlane_b32 s9, v255, 23
	s_nop 1
	v_lshl_add_u64 v[0:1], v[0:1], 2, s[8:9]
	global_load_dword v0, v[0:1], off
	s_waitcnt vmcnt(0)
	ds_write_b32 v2, v0

.LBB0_618:
	s_lshr_b32 s1, s89, 5
	s_and_b32 s10, s83, 0xfffff000
	s_and_b32 s1, s1, 7
	s_ashr_i32 s11, s10, 31
	s_mul_i32 s2, s1, 0x600000
	s_lshl_b64 s[12:13], s[10:11], 1
	s_add_u32 s2, s2, s12
	s_addc_u32 s11, 0, s13
	v_readlane_b32 s12, v255, 26
	s_add_u32 s76, s12, s2
	v_readlane_b32 s2, v255, 27
	s_addc_u32 s77, s2, s11
	s_mul_hi_i32 s2, s10, 0x1800
	s_mulk_i32 s10, 0x1800
	s_lshl_b32 s1, s1, 8
	s_or_b32 s1, s10, s1
	v_readlane_b32 s10, v255, 29
	s_add_u32 s10, s10, s1
	v_readlane_b32 s1, v255, 30
	s_addc_u32 s11, s1, s2
	s_and_b32 s20, s90, 0xf80
	s_ashr_i32 s35, s34, 31
	s_mul_i32 s2, s34, 0x1800
	s_mul_hi_i32 s1, s34, 0x1800
	s_add_u32 s2, s18, s2
	s_addc_u32 s1, s19, s1
	s_lshl_b32 s72, s0, 1
	s_add_u32 s26, s2, s72
	s_addc_u32 s40, s1, 0
	s_add_u32 s21, s26, 0x800
	s_addc_u32 s84, s40, 0
	s_mul_i32 s0, s0, 0xc000
	v_readlane_b32 s1, v255, 18
	s_add_u32 s2, s1, s0
	v_readlane_b32 s0, v255, 19
	s_addc_u32 s12, s0, 0
	s_lshl_b64 s[0:1], s[34:35], 1
	s_add_u32 s44, s2, s0
	s_addc_u32 s85, s12, s1
	s_add_u32 s41, s26, 0x880
	s_addc_u32 s46, s40, 0
	s_cmp_lt_u32 s3, 18
	s_cselect_b64 s[48:49], -1, 0
	s_cmp_lt_u32 s3, 36
	s_cselect_b64 s[52:53], -1, 0
	s_and_b64 s[0:1], s[52:53], exec
	s_cselect_b32 s2, s85, s84
	s_cselect_b32 s12, s44, s21
	s_and_b64 s[0:1], s[48:49], exec
	s_cselect_b32 s12, s41, s12
	s_cselect_b32 s2, s46, s2
	s_and_b64 s[0:1], s[36:37], exec
	s_cselect_b32 s1, s84, s2
	s_cselect_b32 s0, s21, s12
	s_lshl_b32 s35, s3, 10
	s_lshl_b32 s33, s6, 10
	s_lshl_b32 s93, s7, 10
	s_lshl_b32 s45, s8, 10
	s_lshl_b32 s59, s9, 10
	s_add_i32 s82, s35, 0x12000
	s_add_i32 s2, s33, 0x12000
	s_add_i32 s92, s93, 0x12000
	s_add_i32 s97, s45, 0x12000
	s_add_i32 s27, s59, 0x12000
	s_cmp_lt_i32 s3, 4
	s_cselect_b64 s[70:71], -1, 0
	s_and_b64 s[12:13], s[70:71], exec
	s_mov_b32 s16, 0x9000
	s_cselect_b32 s47, s59, s27
	s_cselect_b32 s56, s16, 0x12000
	s_cmp_lt_i32 s3, 12
	s_cselect_b64 s[24:25], -1, 0
	s_and_b64 s[12:13], s[24:25], exec
	s_cselect_b32 s14, s45, s97
	s_cselect_b32 s57, s16, 0x12000
	s_cmp_lt_i32 s3, 20
	s_cselect_b64 s[42:43], -1, 0
	s_and_b64 s[12:13], s[42:43], exec
	s_cselect_b32 s15, s93, s92
	s_cselect_b32 s78, s16, 0x12000
	s_cmp_lt_i32 s3, 28
	s_cselect_b64 s[64:65], -1, 0
	s_and_b64 s[12:13], s[64:65], exec
	s_cselect_b32 s38, s33, s2
	s_cselect_b32 s79, s16, 0x12000
	s_cmp_lt_i32 s3, 36
	s_cselect_b64 s[54:55], -1, 0
	s_and_b64 s[12:13], s[54:55], exec
	s_cselect_b32 s12, s35, s82
	s_cselect_b32 s80, s16, 0x12000
	s_add_i32 m0, s12, 0
	s_cmp_lt_u32 s6, 18
	s_cselect_b64 s[66:67], -1, 0
	s_cmp_lt_u32 s6, 36
	s_cselect_b64 s[28:29], -1, 0
	global_load_lds_dwordx4 v176, s[0:1]
	s_and_b64 s[0:1], s[28:29], exec
	s_cselect_b32 s6, s85, s84
	s_cselect_b32 s12, s44, s21
	s_and_b64 s[0:1], s[66:67], exec
	s_cselect_b32 s12, s41, s12
	s_cselect_b32 s6, s46, s6
	s_and_b64 s[0:1], s[50:51], exec
	s_cselect_b32 s1, s84, s6
	s_cselect_b32 s0, s21, s12
	s_add_i32 m0, s38, 0
	s_cmp_lt_u32 s7, 18
	s_cselect_b64 s[38:39], -1, 0
	s_cmp_lt_u32 s7, 36
	s_cselect_b64 s[60:61], -1, 0
	global_load_lds_dwordx4 v148, s[0:1]
	s_and_b64 s[0:1], s[60:61], exec
	s_cselect_b32 s6, s85, s84
	s_cselect_b32 s7, s44, s21
	s_and_b64 s[0:1], s[38:39], exec
	s_cselect_b32 s7, s41, s7
	s_cselect_b32 s6, s46, s6
	s_and_b64 s[0:1], s[62:63], exec
	s_cselect_b32 s1, s84, s6
	s_cselect_b32 s0, s21, s7
	s_add_i32 m0, s15, 0
	s_cmp_lt_u32 s8, 18
	s_cselect_b64 s[12:13], -1, 0
	s_cmp_lt_u32 s8, 36
	s_cselect_b64 s[6:7], -1, 0
	global_load_lds_dwordx4 v150, s[0:1]
	s_and_b64 s[0:1], s[6:7], exec
	s_cselect_b32 s8, s85, s84
	s_cselect_b32 s15, s44, s21
	s_and_b64 s[0:1], s[12:13], exec
	s_cselect_b32 s15, s41, s15
	s_cselect_b32 s8, s46, s8
	s_and_b64 s[0:1], s[22:23], exec
	s_cselect_b32 s1, s84, s8
	s_cselect_b32 s0, s21, s15
	s_add_i32 m0, s14, 0
	s_cmp_lt_u32 s9, 18
	global_load_lds_dwordx4 v152, s[0:1]
	s_cselect_b64 s[0:1], -1, 0
	s_cmp_lt_u32 s9, 36
	s_cselect_b64 s[14:15], -1, 0
	s_and_b64 s[8:9], s[14:15], exec
	s_cselect_b32 s81, s85, s84
	s_cselect_b32 s86, s44, s21
	s_and_b64 s[8:9], s[0:1], exec
	s_cselect_b32 s41, s41, s86
	s_cselect_b32 s46, s46, s81
	s_and_b64 s[8:9], s[68:69], exec
	s_cselect_b32 s9, s84, s46
	s_cselect_b32 s8, s21, s41
	s_add_i32 m0, s47, 0
	s_add_u32 s81, s26, 0x60800
	s_addc_u32 s86, s40, 0
	s_add_u32 s87, s44, 0x80
	s_addc_u32 s91, s85, 0
	s_add_u32 s94, s26, 0x60880
	s_addc_u32 vcc_lo, s40, 0
	global_load_lds_dwordx4 v154, s[8:9]
	s_and_b64 s[8:9], s[52:53], exec
	s_cselect_b32 s26, s91, s86
	s_cselect_b32 s40, s87, s81
	s_and_b64 s[8:9], s[48:49], exec
	s_cselect_b32 s40, s94, s40
	s_cselect_b32 s26, vcc_lo, s26
	s_and_b64 s[8:9], s[36:37], exec
	s_cselect_b32 s9, s86, s26
	s_cselect_b32 s8, s81, s40
	s_add_i32 s26, s35, 0
	s_add_i32 m0, s26, s80
	v_lshlrev_b32_e32 v0, 2, v141
	global_load_lds_dwordx4 v176, s[8:9]
	s_and_b64 s[8:9], s[28:29], exec
	s_cselect_b32 s40, s91, s86
	s_cselect_b32 s41, s87, s81
	s_and_b64 s[8:9], s[66:67], exec
	s_cselect_b32 s46, s94, s41
	s_cselect_b32 s40, vcc_lo, s40
	s_and_b64 s[8:9], s[50:51], exec
	s_cselect_b32 s41, s86, s40
	s_cselect_b32 s40, s81, s46
	s_add_i32 s8, s33, 0
	s_add_i32 m0, s8, s79
	v_lshrrev_b32_e32 v2, 1, v141
	global_load_lds_dwordx4 v148, s[40:41]
	s_and_b64 s[40:41], s[60:61], exec
	s_cselect_b32 s9, s91, s86
	s_cselect_b32 s46, s87, s81
	s_and_b64 s[40:41], s[38:39], exec
	s_cselect_b32 s46, s94, s46
	s_cselect_b32 s9, vcc_lo, s9
	s_and_b64 s[40:41], s[62:63], exec
	s_cselect_b32 s41, s86, s9
	s_cselect_b32 s40, s81, s46
	s_add_i32 s9, s93, 0
	s_add_i32 m0, s9, s78
	v_and_b32_e32 v1, 3, v141
	global_load_lds_dwordx4 v150, s[40:41]
	s_and_b64 s[40:41], s[6:7], exec
	s_cselect_b32 s46, s91, s86
	s_cselect_b32 s47, s87, s81
	s_and_b64 s[40:41], s[12:13], exec
	s_cselect_b32 s78, s94, s47
	s_cselect_b32 s46, vcc_lo, s46
	s_and_b64 s[40:41], s[22:23], exec
	s_cselect_b32 s47, s86, s46
	s_cselect_b32 s46, s81, s78
	s_add_i32 s40, s45, 0
	s_add_i32 m0, s40, s57
	v_and_b32_e32 v2, 12, v2
	global_load_lds_dwordx4 v152, s[46:47]
	s_and_b64 s[46:47], s[14:15], exec
	s_cselect_b32 s41, s91, s86
	s_cselect_b32 s57, s87, s81
	s_and_b64 s[46:47], s[0:1], exec
	s_cselect_b32 s57, s94, s57
	s_cselect_b32 s41, vcc_lo, s41
	s_and_b64 s[46:47], s[68:69], exec
	s_cselect_b32 s47, s86, s41
	s_cselect_b32 s46, s81, s57
	s_add_i32 s41, s59, 0
	s_add_i32 m0, s41, s56
	s_or_b32 s86, s88, s5
	global_load_lds_dwordx4 v154, s[46:47]
	s_cmpk_lt_u32 s4, 0x100
	s_waitcnt vmcnt(0)
	v_and_b32_e32 v0, 16, v0
	s_cselect_b64 s[16:17], -1, 0
	v_or3_b32 v0, v0, v1, v2
	v_writelane_b32 v255, s16, 33
	v_mov_b32_e32 v149, v177
	v_mov_b32_e32 v151, v177
	v_mov_b32_e32 v153, v177
	v_mov_b32_e32 v155, v177
	v_or_b32_e32 v161, s86, v140
	v_writelane_b32 v255, s17, 34
	s_cmpk_gt_u32 s4, 0xff
	s_mov_b64 s[4:5], -1
	v_mul_u32_u24_e32 v162, 0x90, v0
	s_waitcnt vmcnt(0) lgkmcnt(0)
	s_barrier
	s_cbranch_scc0 .LBB0_634
	s_mul_i32 s94, s58, 0x2400
	s_add_i32 s4, s94, 0
	s_waitcnt lgkmcnt(0)
	s_barrier
	v_add3_u32 v2, s4, v162, v146
	ds_read_b128 v[32:35], v2
	ds_read_b128 v[36:39], v2 offset:32
	ds_read_b128 v[40:43], v2 offset:4608
	ds_read_b128 v[44:47], v2 offset:4640
	s_add_u32 s46, s21, 0xc0000
	s_addc_u32 s47, s84, 0
	s_add_u32 s56, s44, 0x100
	s_addc_u32 s57, s85, 0
	s_add_u32 s78, s21, 0xc0080
	s_addc_u32 s79, s84, 0
	s_and_b64 s[4:5], s[52:53], exec
	s_cselect_b32 s80, s57, s47
	s_cselect_b32 s81, s56, s46
	s_and_b64 s[4:5], s[48:49], exec
	s_cselect_b32 s81, s78, s81
	s_cselect_b32 s80, s79, s80
	s_and_b64 s[4:5], s[36:37], exec
	s_cselect_b32 s5, s47, s80
	s_cselect_b32 s4, s46, s81
	s_add_i32 m0, s26, 0x12000
	v_lshl_add_u64 v[0:1], s[4:5], 0, v[176:177]
	s_and_b64 s[4:5], s[28:29], exec
	s_cselect_b32 s80, s57, s47
	s_cselect_b32 s81, s56, s46
	s_and_b64 s[4:5], s[66:67], exec
	s_cselect_b32 s81, s78, s81
	s_cselect_b32 s80, s79, s80
	s_and_b64 s[4:5], s[50:51], exec
	global_load_lds_dwordx4 v[0:1], off
	s_cselect_b32 s5, s47, s80
	s_cselect_b32 s4, s46, s81
	s_add_i32 m0, s8, 0x12000
	v_lshl_add_u64 v[0:1], s[4:5], 0, v[148:149]
	s_and_b64 s[4:5], s[60:61], exec
	s_cselect_b32 s8, s57, s47
	s_cselect_b32 s80, s56, s46
	s_and_b64 s[4:5], s[38:39], exec
	s_cselect_b32 s80, s78, s80
	s_cselect_b32 s8, s79, s8
	s_and_b64 s[4:5], s[62:63], exec
	global_load_lds_dwordx4 v[0:1], off
	s_cselect_b32 s5, s47, s8
	s_cselect_b32 s4, s46, s80
	s_add_i32 m0, s9, 0x12000
	v_lshl_add_u64 v[0:1], s[4:5], 0, v[150:151]
	s_and_b64 s[4:5], s[6:7], exec
	s_cselect_b32 s8, s57, s47
	s_cselect_b32 s9, s56, s46
	s_and_b64 s[4:5], s[12:13], exec
	s_cselect_b32 s9, s78, s9
	s_cselect_b32 s8, s79, s8
	s_and_b64 s[4:5], s[22:23], exec
	global_load_lds_dwordx4 v[0:1], off
	s_cselect_b32 s5, s47, s8
	s_cselect_b32 s4, s46, s9
	s_add_i32 m0, s40, 0x12000
	v_lshl_add_u64 v[0:1], s[4:5], 0, v[152:153]
	s_and_b64 s[4:5], s[14:15], exec
	s_cselect_b32 s8, s57, s47
	s_cselect_b32 s9, s56, s46
	s_and_b64 s[4:5], s[0:1], exec
	s_cselect_b32 s9, s78, s9
	s_cselect_b32 s8, s79, s8
	s_and_b64 s[4:5], s[68:69], exec
	s_cselect_b32 s5, s47, s8
	s_cselect_b32 s4, s46, s9
	global_load_lds_dwordx4 v[0:1], off
	v_lshl_add_u64 v[0:1], s[4:5], 0, v[154:155]
	s_add_i32 m0, s41, 0x12000
	s_nop 0
	global_load_lds_dwordx4 v[0:1], off
	ds_read_b128 v[48:51], v2 offset:64
	ds_read_b128 v[52:55], v2 offset:96
	ds_read_b128 v[56:59], v2 offset:4672
	ds_read_b128 v[60:63], v2 offset:4704
	s_cmpk_gt_u32 s86, 0xbe
	s_cselect_b64 vcc, -1, 0
	v_cndmask_b32_e32 v142, 0, v159, vcc
	s_mov_b32 s4, 0x7149f2ca
	v_cmp_neq_f32_e64 s[4:5], s4, v142
	s_and_b64 vcc, exec, vcc
	s_nop 0
	v_cndmask_b32_e64 v0, 0, v142, s[4:5]
	v_mov_b32_e32 v1, v0
	v_mov_b32_e32 v2, v0
	v_mov_b32_e32 v3, v0
	v_mov_b32_e32 v4, v0
	v_mov_b32_e32 v5, v0
	v_mov_b32_e32 v6, v0
	v_mov_b32_e32 v7, v0
	v_mov_b32_e32 v8, v0
	v_mov_b32_e32 v9, v0
	v_mov_b32_e32 v10, v0
	v_mov_b32_e32 v11, v0
	v_mov_b32_e32 v12, v0
	v_mov_b32_e32 v13, v0
	v_mov_b32_e32 v14, v0
	v_mov_b32_e32 v15, v0
	s_waitcnt lgkmcnt(0)
	s_nop 0
	v_mfma_f32_32x32x16_bf16 v[16:31], v[32:35], v[112:115], v[0:15]
	v_mfma_f32_32x32x16_bf16 v[0:15], v[40:43], v[112:115], v[0:15]
	v_mfma_f32_32x32x16_bf16 v[16:31], v[36:39], v[116:119], v[16:31]
	v_mfma_f32_32x32x16_bf16 v[0:15], v[44:47], v[116:119], v[0:15]
	v_mfma_f32_32x32x16_bf16 v[16:31], v[48:51], v[120:123], v[16:31]
	v_mfma_f32_32x32x16_bf16 v[0:15], v[56:59], v[120:123], v[0:15]
	v_mfma_f32_32x32x16_bf16 v[16:31], v[52:55], v[124:127], v[16:31]
	v_mfma_f32_32x32x16_bf16 v[0:15], v[60:63], v[124:127], v[0:15]
	s_cbranch_vccnz .LBB0_621
	v_sub_u32_e32 v56, v146, v161
	s_add_i32 s4, 0, 0x20180
	v_max_i32_e32 v34, 0xffffff7f, v56
	v_lshl_add_u32 v36, v34, 2, s4
	v_max_i32_e32 v34, 0xffffff7e, v56
	v_max_i32_e32 v32, 0xffffff80, v56
	v_max_i32_e32 v33, 0xffffff60, v56
	v_max_i32_e32 v35, 0xffffff5f, v56
	v_max_i32_e32 v37, 0xffffff5e, v56
	v_lshl_add_u32 v38, v34, 2, s4
	v_max_i32_e32 v34, 0xffffff7d, v56
	v_max_i32_e32 v39, 0xffffff5d, v56
	v_max_i32_e32 v42, 0xffffff7b, v56
	v_lshl_add_u32 v32, v32, 2, s4
	v_lshl_add_u32 v33, v33, 2, s4
	v_lshl_add_u32 v35, v35, 2, s4
	v_lshl_add_u32 v37, v37, 2, s4
	v_lshl_add_u32 v40, v34, 2, s4
	v_lshl_add_u32 v39, v39, 2, s4
	v_lshl_add_u32 v44, v42, 2, s4
	v_max_i32_e32 v42, 0xffffff7a, v56
	ds_read_b32 v32, v32 offset:512
	ds_read_b32 v34, v33 offset:640
	ds_read_b32 v33, v36 offset:516
	ds_read_b32 v35, v35 offset:644
	ds_read_b32 v36, v38 offset:520
	ds_read_b32 v38, v37 offset:648
	ds_read_b32 v37, v40 offset:524
	ds_read_b32 v39, v39 offset:652
	v_max_i32_e32 v40, 0xffffff7c, v56
	v_max_i32_e32 v41, 0xffffff5c, v56
	v_max_i32_e32 v43, 0xffffff5b, v56
	v_max_i32_e32 v45, 0xffffff5a, v56
	v_lshl_add_u32 v46, v42, 2, s4
	v_max_i32_e32 v42, 0xffffff79, v56
	v_max_i32_e32 v47, 0xffffff59, v56
	v_max_i32_e32 v50, 0xffffff77, v56
	v_lshl_add_u32 v40, v40, 2, s4
	v_lshl_add_u32 v41, v41, 2, s4
	v_lshl_add_u32 v43, v43, 2, s4
	v_lshl_add_u32 v45, v45, 2, s4
	v_lshl_add_u32 v48, v42, 2, s4
	v_lshl_add_u32 v47, v47, 2, s4
	v_lshl_add_u32 v52, v50, 2, s4
	v_max_i32_e32 v50, 0xffffff76, v56
	ds_read_b32 v40, v40 offset:528
	ds_read_b32 v42, v41 offset:656
	ds_read_b32 v41, v44 offset:532
	ds_read_b32 v43, v43 offset:660
	ds_read_b32 v44, v46 offset:536
	ds_read_b32 v46, v45 offset:664
	ds_read_b32 v45, v48 offset:540
	ds_read_b32 v47, v47 offset:668
	v_max_i32_e32 v48, 0xffffff78, v56
	v_max_i32_e32 v49, 0xffffff58, v56
	v_max_i32_e32 v51, 0xffffff57, v56
	v_max_i32_e32 v53, 0xffffff56, v56
	v_lshl_add_u32 v54, v50, 2, s4
	v_max_i32_e32 v50, 0xffffff75, v56
	v_max_i32_e32 v55, 0xffffff55, v56
	v_lshl_add_u32 v48, v48, 2, s4
	v_lshl_add_u32 v49, v49, 2, s4
	v_lshl_add_u32 v51, v51, 2, s4
	v_lshl_add_u32 v53, v53, 2, s4
	v_lshl_add_u32 v57, v50, 2, s4
	v_lshl_add_u32 v55, v55, 2, s4
	v_max_i32_e32 v60, 0xffffff53, v56
	v_max_i32_e32 v61, 0xffffff52, v56
	ds_read_b32 v48, v48 offset:544
	ds_read_b32 v50, v49 offset:672
	ds_read_b32 v49, v52 offset:548
	ds_read_b32 v51, v51 offset:676
	ds_read_b32 v52, v54 offset:552
	ds_read_b32 v54, v53 offset:680
	ds_read_b32 v53, v57 offset:556
	ds_read_b32 v55, v55 offset:684
	v_max_i32_e32 v57, 0xffffff74, v56
	v_max_i32_e32 v58, 0xffffff54, v56
	v_max_i32_e32 v59, 0xffffff73, v56
	v_lshl_add_u32 v64, v60, 2, s4
	v_max_i32_e32 v60, 0xffffff72, v56
	v_lshl_add_u32 v62, v61, 2, s4
	v_max_i32_e32 v61, 0xffffff71, v56
	v_max_i32_e32 v56, 0xffffff51, v56
	v_lshl_add_u32 v57, v57, 2, s4
	v_lshl_add_u32 v58, v58, 2, s4
	v_lshl_add_u32 v59, v59, 2, s4
	v_lshl_add_u32 v60, v60, 2, s4
	v_lshl_add_u32 v61, v61, 2, s4
	v_lshl_add_u32 v63, v56, 2, s4
	ds_read_b32 v56, v57 offset:560
	ds_read_b32 v58, v58 offset:688
	ds_read_b32 v60, v60 offset:568
	ds_read_b32 v61, v61 offset:572
	ds_read_b32 v57, v59 offset:564
	ds_read_b32 v63, v63 offset:700
	ds_read_b32 v62, v62 offset:696
	ds_read_b32 v59, v64 offset:692
	s_waitcnt lgkmcnt(0)
	v_pk_add_f32 v[30:31], v[30:31], v[60:61]
	v_pk_add_f32 v[28:29], v[28:29], v[56:57]
	v_pk_add_f32 v[26:27], v[26:27], v[52:53]
	v_pk_add_f32 v[24:25], v[24:25], v[48:49]
	v_pk_add_f32 v[22:23], v[22:23], v[44:45]
	v_pk_add_f32 v[20:21], v[20:21], v[40:41]
	v_pk_add_f32 v[18:19], v[18:19], v[36:37]
	v_pk_add_f32 v[16:17], v[16:17], v[32:33]
	v_pk_add_f32 v[14:15], v[14:15], v[62:63]
	v_pk_add_f32 v[12:13], v[12:13], v[58:59]
	v_pk_add_f32 v[10:11], v[10:11], v[54:55]
	v_pk_add_f32 v[8:9], v[8:9], v[50:51]
	v_pk_add_f32 v[6:7], v[6:7], v[46:47]
	v_pk_add_f32 v[4:5], v[4:5], v[42:43]
	v_pk_add_f32 v[2:3], v[2:3], v[38:39]
	v_pk_add_f32 v[0:1], v[0:1], v[34:35]

.Lattn_negm_keep_0:
	s_addk_i32 s16, 0xffa1
	s_cmp_lt_u32 s16, 0xfffffea3
	s_nop 0
	s_waitcnt lgkmcnt(7)
	v_mfma_f32_32x32x16_bf16 v[96:111], v[80:83], v[112:115], v[64:79]
	s_waitcnt lgkmcnt(5)
	v_mfma_f32_32x32x16_bf16 v[80:95], v[136:139], v[112:115], v[64:79]
	v_mfma_f32_32x32x16_bf16 v[96:111], v[128:131], v[116:119], v[96:111]
	s_waitcnt lgkmcnt(4)
	v_mfma_f32_32x32x16_bf16 v[80:95], v[132:135], v[116:119], v[80:95]
	s_waitcnt lgkmcnt(3)
	v_mfma_f32_32x32x16_bf16 v[96:111], v[166:169], v[120:123], v[96:111]
	s_waitcnt lgkmcnt(1)
	v_mfma_f32_32x32x16_bf16 v[80:95], v[178:181], v[120:123], v[80:95]
	v_mfma_f32_32x32x16_bf16 v[96:111], v[170:173], v[124:127], v[96:111]
	s_waitcnt lgkmcnt(0)
	v_mfma_f32_32x32x16_bf16 v[80:95], v[182:185], v[124:127], v[80:95]
	s_cbranch_scc1 .LBB0_627
	v_add_u32_e32 v180, s87, v164
	s_mov_b32 s80, 0x20380
	v_lshl_add_u32 v250, v180, 2, s80
	ds_read2_b32 v[128:129], v250 offset0:0 offset1:1
	ds_read2_b32 v[132:133], v250 offset0:2 offset1:3
	ds_read2_b32 v[136:137], v250 offset0:4 offset1:5
	ds_read2_b32 v[166:167], v250 offset0:6 offset1:7
	ds_read2_b32 v[170:171], v250 offset0:8 offset1:9
	ds_read2_b32 v[174:175], v250 offset0:10 offset1:11
	ds_read2_b32 v[180:181], v250 offset0:12 offset1:13
	ds_read2_b32 v[184:185], v250 offset0:14 offset1:15
	ds_read2_b32 v[130:131], v250 offset0:32 offset1:33
	ds_read2_b32 v[134:135], v250 offset0:34 offset1:35
	ds_read2_b32 v[138:139], v250 offset0:36 offset1:37
	ds_read2_b32 v[168:169], v250 offset0:38 offset1:39
	ds_read2_b32 v[172:173], v250 offset0:40 offset1:41
	ds_read2_b32 v[178:179], v250 offset0:42 offset1:43
	ds_read2_b32 v[182:183], v250 offset0:44 offset1:45
	ds_read2_b32 v[186:187], v250 offset0:46 offset1:47
	s_waitcnt lgkmcnt(0)
	v_pk_add_f32 v[110:111], v[110:111], v[184:185]
	v_pk_add_f32 v[108:109], v[108:109], v[180:181]
	v_pk_add_f32 v[106:107], v[106:107], v[174:175]
	v_pk_add_f32 v[104:105], v[104:105], v[170:171]
	v_pk_add_f32 v[102:103], v[102:103], v[166:167]
	v_pk_add_f32 v[100:101], v[100:101], v[136:137]
	v_pk_add_f32 v[98:99], v[98:99], v[132:133]
	v_pk_add_f32 v[96:97], v[96:97], v[128:129]
	v_pk_add_f32 v[94:95], v[94:95], v[186:187]
	v_pk_add_f32 v[92:93], v[92:93], v[182:183]
	v_pk_add_f32 v[90:91], v[90:91], v[178:179]
	v_pk_add_f32 v[88:89], v[88:89], v[172:173]
	v_pk_add_f32 v[86:87], v[86:87], v[168:169]
	v_pk_add_f32 v[84:85], v[84:85], v[138:139]
	v_pk_add_f32 v[82:83], v[82:83], v[134:135]
	v_pk_add_f32 v[80:81], v[80:81], v[130:131]

.LBB0_634:
	s_and_b64 vcc, exec, s[4:5]
	v_readlane_b32 s94, v254, 58
	s_mov_b32 s92, 0x12000
	s_mov_b32 s93, 0x14000
	s_mov_b32 s97, 0x16000
	s_movk_i32 s68, 0x4000
	s_movk_i32 s69, 0x6000
	s_mov_b32 s70, 0xc000
	s_mov_b32 s71, 0x18000
	s_mov_b32 s66, 0x8000
	s_mov_b32 s67, 0x1c000
	s_mov_b32 s65, 0x1e000
	s_movk_i32 s81, 0x1800
	s_mov_b32 s91, 0x38e38e39
	s_cbranch_vccz .LBB0_650
	v_add3_u32 v0, 0, v162, v146
	ds_read_b128 v[32:35], v0
	ds_read_b128 v[36:39], v0 offset:32
	ds_read_b128 v[40:43], v0 offset:4608
	ds_read_b128 v[44:47], v0 offset:4640
	ds_read_b128 v[48:51], v0 offset:64
	ds_read_b128 v[52:55], v0 offset:96
	ds_read_b128 v[56:59], v0 offset:4672
	ds_read_b128 v[60:63], v0 offset:4704
	s_cmpk_gt_u32 s86, 0xbe
	s_cselect_b64 vcc, -1, 0
	v_cndmask_b32_e32 v163, 0, v159, vcc
	s_mov_b32 s0, 0x7149f2ca
	v_cmp_neq_f32_e64 s[4:5], s0, v163
	s_and_b64 vcc, exec, vcc
	s_nop 0
	v_cndmask_b32_e64 v0, 0, v163, s[4:5]
	v_mov_b32_e32 v1, v0
	v_mov_b32_e32 v2, v0
	v_mov_b32_e32 v3, v0
	v_mov_b32_e32 v4, v0
	v_mov_b32_e32 v5, v0
	v_mov_b32_e32 v6, v0
	v_mov_b32_e32 v7, v0
	v_mov_b32_e32 v8, v0
	v_mov_b32_e32 v9, v0
	v_mov_b32_e32 v10, v0
	v_mov_b32_e32 v11, v0
	v_mov_b32_e32 v12, v0
	v_mov_b32_e32 v13, v0
	v_mov_b32_e32 v14, v0
	v_mov_b32_e32 v15, v0
	s_waitcnt lgkmcnt(0)
	s_nop 0
	v_mfma_f32_32x32x16_bf16 v[16:31], v[32:35], v[112:115], v[0:15]
	v_mfma_f32_32x32x16_bf16 v[0:15], v[40:43], v[112:115], v[0:15]
	v_mfma_f32_32x32x16_bf16 v[16:31], v[36:39], v[116:119], v[16:31]
	v_mfma_f32_32x32x16_bf16 v[0:15], v[44:47], v[116:119], v[0:15]
	v_mfma_f32_32x32x16_bf16 v[16:31], v[48:51], v[120:123], v[16:31]
	v_mfma_f32_32x32x16_bf16 v[0:15], v[56:59], v[120:123], v[0:15]
	v_mfma_f32_32x32x16_bf16 v[16:31], v[52:55], v[124:127], v[16:31]
	v_mfma_f32_32x32x16_bf16 v[0:15], v[60:63], v[124:127], v[0:15]
	s_cbranch_vccnz .LBB0_637
	v_sub_u32_e32 v56, v146, v161
	s_add_i32 s0, 0, 0x20180
	v_max_i32_e32 v34, 0xffffff7f, v56
	v_lshl_add_u32 v36, v34, 2, s0
	v_max_i32_e32 v34, 0xffffff7e, v56
	v_max_i32_e32 v32, 0xffffff80, v56
	v_max_i32_e32 v33, 0xffffff60, v56
	v_max_i32_e32 v35, 0xffffff5f, v56
	v_max_i32_e32 v37, 0xffffff5e, v56
	v_lshl_add_u32 v38, v34, 2, s0
	v_max_i32_e32 v34, 0xffffff7d, v56
	v_max_i32_e32 v39, 0xffffff5d, v56
	v_max_i32_e32 v42, 0xffffff7b, v56
	v_lshl_add_u32 v32, v32, 2, s0
	v_lshl_add_u32 v33, v33, 2, s0
	v_lshl_add_u32 v35, v35, 2, s0
	v_lshl_add_u32 v37, v37, 2, s0
	v_lshl_add_u32 v40, v34, 2, s0
	v_lshl_add_u32 v39, v39, 2, s0
	v_lshl_add_u32 v44, v42, 2, s0
	v_max_i32_e32 v42, 0xffffff7a, v56
	ds_read_b32 v32, v32 offset:512
	ds_read_b32 v34, v33 offset:640
	ds_read_b32 v33, v36 offset:516
	ds_read_b32 v35, v35 offset:644
	ds_read_b32 v36, v38 offset:520
	ds_read_b32 v38, v37 offset:648
	ds_read_b32 v37, v40 offset:524
	ds_read_b32 v39, v39 offset:652
	v_max_i32_e32 v40, 0xffffff7c, v56
	v_max_i32_e32 v41, 0xffffff5c, v56
	v_max_i32_e32 v43, 0xffffff5b, v56
	v_max_i32_e32 v45, 0xffffff5a, v56
	v_lshl_add_u32 v46, v42, 2, s0
	v_max_i32_e32 v42, 0xffffff79, v56
	v_max_i32_e32 v47, 0xffffff59, v56
	v_max_i32_e32 v50, 0xffffff77, v56
	v_lshl_add_u32 v40, v40, 2, s0
	v_lshl_add_u32 v41, v41, 2, s0
	v_lshl_add_u32 v43, v43, 2, s0
	v_lshl_add_u32 v45, v45, 2, s0
	v_lshl_add_u32 v48, v42, 2, s0
	v_lshl_add_u32 v47, v47, 2, s0
	v_lshl_add_u32 v52, v50, 2, s0
	v_max_i32_e32 v50, 0xffffff76, v56
	ds_read_b32 v40, v40 offset:528
	ds_read_b32 v42, v41 offset:656
	ds_read_b32 v41, v44 offset:532
	ds_read_b32 v43, v43 offset:660
	ds_read_b32 v44, v46 offset:536
	ds_read_b32 v46, v45 offset:664
	ds_read_b32 v45, v48 offset:540
	ds_read_b32 v47, v47 offset:668
	v_max_i32_e32 v48, 0xffffff78, v56
	v_max_i32_e32 v49, 0xffffff58, v56
	v_max_i32_e32 v51, 0xffffff57, v56
	v_max_i32_e32 v53, 0xffffff56, v56
	v_lshl_add_u32 v54, v50, 2, s0
	v_max_i32_e32 v50, 0xffffff75, v56
	v_max_i32_e32 v55, 0xffffff55, v56
	v_lshl_add_u32 v48, v48, 2, s0
	v_lshl_add_u32 v49, v49, 2, s0
	v_lshl_add_u32 v51, v51, 2, s0
	v_lshl_add_u32 v53, v53, 2, s0
	v_lshl_add_u32 v57, v50, 2, s0
	v_lshl_add_u32 v55, v55, 2, s0
	v_max_i32_e32 v60, 0xffffff53, v56
	v_max_i32_e32 v61, 0xffffff52, v56
	ds_read_b32 v48, v48 offset:544
	ds_read_b32 v50, v49 offset:672
	ds_read_b32 v49, v52 offset:548
	ds_read_b32 v51, v51 offset:676
	ds_read_b32 v52, v54 offset:552
	ds_read_b32 v54, v53 offset:680
	ds_read_b32 v53, v57 offset:556
	ds_read_b32 v55, v55 offset:684
	v_max_i32_e32 v57, 0xffffff74, v56
	v_max_i32_e32 v58, 0xffffff54, v56
	v_max_i32_e32 v59, 0xffffff73, v56
	v_lshl_add_u32 v64, v60, 2, s0
	v_max_i32_e32 v60, 0xffffff72, v56
	v_lshl_add_u32 v62, v61, 2, s0
	v_max_i32_e32 v61, 0xffffff71, v56
	v_max_i32_e32 v56, 0xffffff51, v56
	v_lshl_add_u32 v57, v57, 2, s0
	v_lshl_add_u32 v58, v58, 2, s0
	v_lshl_add_u32 v59, v59, 2, s0
	v_lshl_add_u32 v60, v60, 2, s0
	v_lshl_add_u32 v61, v61, 2, s0
	v_lshl_add_u32 v63, v56, 2, s0
	ds_read_b32 v56, v57 offset:560
	ds_read_b32 v58, v58 offset:688
	ds_read_b32 v60, v60 offset:568
	ds_read_b32 v61, v61 offset:572
	ds_read_b32 v57, v59 offset:564
	ds_read_b32 v63, v63 offset:700
	ds_read_b32 v62, v62 offset:696
	ds_read_b32 v59, v64 offset:692
	s_waitcnt lgkmcnt(0)
	v_pk_add_f32 v[30:31], v[30:31], v[60:61]
	v_pk_add_f32 v[28:29], v[28:29], v[56:57]
	v_pk_add_f32 v[26:27], v[26:27], v[52:53]
	v_pk_add_f32 v[24:25], v[24:25], v[48:49]
	v_pk_add_f32 v[22:23], v[22:23], v[44:45]
	v_pk_add_f32 v[20:21], v[20:21], v[40:41]
	v_pk_add_f32 v[18:19], v[18:19], v[36:37]
	v_pk_add_f32 v[16:17], v[16:17], v[32:33]
	v_pk_add_f32 v[14:15], v[14:15], v[62:63]
	v_pk_add_f32 v[12:13], v[12:13], v[58:59]
	v_pk_add_f32 v[10:11], v[10:11], v[54:55]
	v_pk_add_f32 v[8:9], v[8:9], v[50:51]
	v_pk_add_f32 v[6:7], v[6:7], v[46:47]
	v_pk_add_f32 v[4:5], v[4:5], v[42:43]
	v_pk_add_f32 v[2:3], v[2:3], v[38:39]
	v_pk_add_f32 v[0:1], v[0:1], v[34:35]

.Lattn_negm_keep_1:
	s_addk_i32 s51, 0xffa1
	s_cmp_lt_u32 s51, 0xfffffea3
	s_nop 0
	s_waitcnt lgkmcnt(7)
	v_mfma_f32_32x32x16_bf16 v[96:111], v[80:83], v[112:115], v[64:79]
	s_waitcnt lgkmcnt(5)
	v_mfma_f32_32x32x16_bf16 v[80:95], v[132:135], v[112:115], v[64:79]
	v_mfma_f32_32x32x16_bf16 v[96:111], v[128:131], v[116:119], v[96:111]
	s_waitcnt lgkmcnt(4)
	v_mfma_f32_32x32x16_bf16 v[80:95], v[136:139], v[116:119], v[80:95]
	s_waitcnt lgkmcnt(3)
	v_mfma_f32_32x32x16_bf16 v[96:111], v[140:143], v[120:123], v[96:111]
	s_waitcnt lgkmcnt(1)
	v_mfma_f32_32x32x16_bf16 v[80:95], v[172:175], v[120:123], v[80:95]
	v_mfma_f32_32x32x16_bf16 v[96:111], v[168:171], v[124:127], v[96:111]
	s_waitcnt lgkmcnt(0)
	v_mfma_f32_32x32x16_bf16 v[80:95], v[178:181], v[124:127], v[80:95]
	s_cbranch_scc1 .LBB0_641
	v_add_u32_e32 v178, s20, v166
	s_mov_b32 s51, 0x20380
	v_lshl_add_u32 v250, v178, 2, s51
	ds_read2_b32 v[128:129], v250 offset0:0 offset1:1
	ds_read2_b32 v[132:133], v250 offset0:2 offset1:3
	ds_read2_b32 v[136:137], v250 offset0:4 offset1:5
	ds_read2_b32 v[140:141], v250 offset0:6 offset1:7
	ds_read2_b32 v[168:169], v250 offset0:8 offset1:9
	ds_read2_b32 v[172:173], v250 offset0:10 offset1:11
	ds_read2_b32 v[178:179], v250 offset0:12 offset1:13
	ds_read2_b32 v[182:183], v250 offset0:14 offset1:15
	ds_read2_b32 v[130:131], v250 offset0:32 offset1:33
	ds_read2_b32 v[134:135], v250 offset0:34 offset1:35
	ds_read2_b32 v[138:139], v250 offset0:36 offset1:37
	ds_read2_b32 v[142:143], v250 offset0:38 offset1:39
	ds_read2_b32 v[170:171], v250 offset0:40 offset1:41
	ds_read2_b32 v[174:175], v250 offset0:42 offset1:43
	ds_read2_b32 v[180:181], v250 offset0:44 offset1:45
	ds_read2_b32 v[184:185], v250 offset0:46 offset1:47
	s_waitcnt lgkmcnt(0)
	v_pk_add_f32 v[110:111], v[110:111], v[182:183]
	v_pk_add_f32 v[108:109], v[108:109], v[178:179]
	v_pk_add_f32 v[106:107], v[106:107], v[172:173]
	v_pk_add_f32 v[104:105], v[104:105], v[168:169]
	v_pk_add_f32 v[102:103], v[102:103], v[140:141]
	v_pk_add_f32 v[100:101], v[100:101], v[136:137]
	v_pk_add_f32 v[98:99], v[98:99], v[132:133]
	v_pk_add_f32 v[96:97], v[96:97], v[128:129]
	v_pk_add_f32 v[94:95], v[94:95], v[184:185]
	v_pk_add_f32 v[92:93], v[92:93], v[180:181]
	v_pk_add_f32 v[90:91], v[90:91], v[174:175]
	v_pk_add_f32 v[88:89], v[88:89], v[170:171]
	v_pk_add_f32 v[86:87], v[86:87], v[142:143]
	v_pk_add_f32 v[84:85], v[84:85], v[138:139]
	v_pk_add_f32 v[82:83], v[82:83], v[134:135]
	v_pk_add_f32 v[80:81], v[80:81], v[130:131]

.LBB0_657:
	s_bfe_u32 s2, s89, 0x30004
	v_mov_b32_e32 v141, v210
	s_movk_i32 s0, 0x1c0
	s_mul_i32 s6, s2, 0x104
	v_readfirstlane_b32 s4, v141
	v_cmp_gt_i32_e32 vcc, s0, v141
	s_and_saveexec_b64 s[0:1], vcc
	s_cbranch_execz .LBB0_659
	v_lshl_add_u32 v0, v141, 2, 0
	v_add_u32_e32 v2, 0x20000, v0
	v_add_u32_e32 v0, 0xffffffa0, v141
	v_max_i32_e32 v0, 0, v0
	v_min_i32_e32 v0, 0x100, v0
	v_add_u32_e32 v0, s6, v0
	v_readlane_b32 s8, v255, 22
	v_ashrrev_i32_e32 v1, 31, v0
	v_readlane_b32 s9, v255, 23
	s_nop 1
	v_lshl_add_u64 v[0:1], v[0:1], 2, s[8:9]
	global_load_dword v0, v[0:1], off
	s_waitcnt vmcnt(0)
	ds_write_b32 v2, v0

.LBB0_679:
	s_and_b32 s10, s87, 0xfffff800
	s_lshr_b32 s1, s89, 4
	s_addk_i32 s10, 0x2000
	s_and_b32 s1, s1, 7
	s_ashr_i32 s11, s10, 31
	s_mul_i32 s2, s1, 0x600000
	s_lshl_b64 s[12:13], s[10:11], 1
	s_add_u32 s2, s2, s12
	s_addc_u32 s11, 0, s13
	v_readlane_b32 s12, v255, 33
	s_add_u32 s40, s12, s2
	v_readlane_b32 s2, v255, 26
	s_addc_u32 s41, s2, s11
	s_mul_hi_i32 s2, s10, 0x1800
	s_mulk_i32 s10, 0x1800
	s_lshl_b32 s1, s1, 8
	s_or_b32 s1, s10, s1
	v_readlane_b32 s10, v255, 28
	s_add_u32 s46, s10, s1
	v_readlane_b32 s1, v255, 29
	s_addc_u32 s47, s1, s2
	s_and_b32 s20, s90, 0x780
	s_ashr_i32 s35, s34, 31
	s_mul_i32 s2, s34, 0x1800
	s_mul_hi_i32 s1, s34, 0x1800
	s_add_u32 s2, s18, s2
	s_addc_u32 s1, s19, s1
	s_lshl_b32 s72, s0, 1
	s_add_u32 s16, s2, s72
	s_addc_u32 s17, s1, 0
	s_add_u32 s21, s16, 0x800
	s_addc_u32 s84, s17, 0
	s_mul_i32 s0, s0, 0xc000
	v_readlane_b32 s1, v255, 18
	s_add_u32 s2, s1, s0
	v_readlane_b32 s0, v255, 19
	s_addc_u32 s10, s0, 0
	s_lshl_b64 s[0:1], s[34:35], 1
	s_add_u32 s44, s2, s0
	s_addc_u32 s85, s10, s1
	s_add_u32 s26, s16, 0x880
	s_addc_u32 s27, s17, 0
	s_cmp_lt_u32 s3, 18
	s_cselect_b64 s[48:49], -1, 0
	s_cmp_lt_u32 s3, 36
	s_cselect_b64 s[52:53], -1, 0
	s_and_b64 s[0:1], s[52:53], exec
	s_cselect_b32 s2, s85, s84
	s_cselect_b32 s10, s44, s21
	s_and_b64 s[0:1], s[48:49], exec
	s_cselect_b32 s10, s26, s10
	s_cselect_b32 s2, s27, s2
	s_and_b64 s[0:1], s[36:37], exec
	s_cselect_b32 s1, s84, s2
	s_cselect_b32 s0, s21, s10
	s_lshl_b32 s35, s3, 10
	s_lshl_b32 s33, s6, 10
	s_lshl_b32 s93, s7, 10
	s_lshl_b32 s45, s8, 10
	s_lshl_b32 s59, s9, 10
	s_add_i32 s82, s35, 0x12000
	s_add_i32 s2, s33, 0x12000
	s_add_i32 s92, s93, 0x12000
	s_add_i32 s97, s45, 0x12000
	s_add_i32 s86, s59, 0x12000
	s_cmp_lt_i32 s3, 4
	s_cselect_b64 s[70:71], -1, 0
	s_and_b64 s[10:11], s[70:71], exec
	s_mov_b32 s15, 0x9000
	s_cselect_b32 s56, s59, s86
	s_cselect_b32 s58, s15, 0x12000
	s_cmp_lt_i32 s3, 12
	s_cselect_b64 s[24:25], -1, 0
	s_and_b64 s[10:11], s[24:25], exec
	s_cselect_b32 s14, s45, s97
	s_cselect_b32 s76, s15, 0x12000
	s_cmp_lt_i32 s3, 20
	s_cselect_b64 s[42:43], -1, 0
	s_and_b64 s[10:11], s[42:43], exec
	s_cselect_b32 s12, s93, s92
	s_cselect_b32 s57, s15, 0x12000
	s_cmp_lt_i32 s3, 28
	s_cselect_b64 s[64:65], -1, 0
	s_and_b64 s[10:11], s[64:65], exec
	s_cselect_b32 s13, s33, s2
	s_cselect_b32 s77, s15, 0x12000
	s_cmp_lt_i32 s3, 36
	s_cselect_b64 s[54:55], -1, 0
	s_and_b64 s[10:11], s[54:55], exec
	s_cselect_b32 s10, s35, s82
	s_cselect_b32 s11, s15, 0x12000
	s_add_i32 m0, s10, 0
	s_cmp_lt_u32 s6, 18
	s_cselect_b64 s[66:67], -1, 0
	s_cmp_lt_u32 s6, 36
	s_cselect_b64 s[28:29], -1, 0
	global_load_lds_dwordx4 v176, s[0:1]
	s_and_b64 s[0:1], s[28:29], exec
	s_cselect_b32 s6, s85, s84
	s_cselect_b32 s10, s44, s21
	s_and_b64 s[0:1], s[66:67], exec
	s_cselect_b32 s10, s26, s10
	s_cselect_b32 s6, s27, s6
	s_and_b64 s[0:1], s[50:51], exec
	s_cselect_b32 s1, s84, s6
	s_cselect_b32 s0, s21, s10
	s_add_i32 m0, s13, 0
	s_cmp_lt_u32 s7, 18
	s_cselect_b64 s[38:39], -1, 0
	s_cmp_lt_u32 s7, 36
	s_cselect_b64 s[60:61], -1, 0
	global_load_lds_dwordx4 v148, s[0:1]
	s_and_b64 s[0:1], s[60:61], exec
	s_cselect_b32 s6, s85, s84
	s_cselect_b32 s7, s44, s21
	s_and_b64 s[0:1], s[38:39], exec
	s_cselect_b32 s7, s26, s7
	s_cselect_b32 s6, s27, s6
	s_and_b64 s[0:1], s[62:63], exec
	s_cselect_b32 s1, s84, s6
	s_cselect_b32 s0, s21, s7
	s_add_i32 m0, s12, 0
	s_cmp_lt_u32 s8, 18
	s_cselect_b64 s[12:13], -1, 0
	s_cmp_lt_u32 s8, 36
	s_cselect_b64 s[6:7], -1, 0
	global_load_lds_dwordx4 v150, s[0:1]
	s_and_b64 s[0:1], s[6:7], exec
	s_cselect_b32 s8, s85, s84
	s_cselect_b32 s10, s44, s21
	s_and_b64 s[0:1], s[12:13], exec
	s_cselect_b32 s10, s26, s10
	s_cselect_b32 s8, s27, s8
	s_and_b64 s[0:1], s[22:23], exec
	s_cselect_b32 s1, s84, s8
	s_cselect_b32 s0, s21, s10
	s_add_i32 m0, s14, 0
	s_cmp_lt_u32 s9, 18
	global_load_lds_dwordx4 v152, s[0:1]
	s_cselect_b64 s[0:1], -1, 0
	s_cmp_lt_u32 s9, 36
	s_cselect_b64 s[14:15], -1, 0
	s_and_b64 s[8:9], s[14:15], exec
	s_cselect_b32 s10, s85, s84
	s_cselect_b32 s78, s44, s21
	s_and_b64 s[8:9], s[0:1], exec
	s_cselect_b32 s26, s26, s78
	s_cselect_b32 s10, s27, s10
	s_and_b64 s[8:9], s[68:69], exec
	s_cselect_b32 s9, s84, s10
	s_cselect_b32 s8, s21, s26
	s_add_i32 m0, s56, 0
	s_add_u32 s27, s16, 0x60800
	s_addc_u32 s78, s17, 0
	s_add_u32 s79, s44, 0x80
	s_addc_u32 s80, s85, 0
	s_add_u32 s16, s16, 0x60880
	s_addc_u32 s17, s17, 0
	global_load_lds_dwordx4 v154, s[8:9]
	s_and_b64 s[8:9], s[52:53], exec
	s_cselect_b32 s10, s80, s78
	s_cselect_b32 s26, s79, s27
	s_and_b64 s[8:9], s[48:49], exec
	s_cselect_b32 s26, s16, s26
	s_cselect_b32 s10, s17, s10
	s_and_b64 s[8:9], s[36:37], exec
	s_cselect_b32 s9, s78, s10
	s_cselect_b32 s8, s27, s26
	s_add_i32 s26, s35, 0
	s_add_i32 m0, s26, s11
	v_lshlrev_b32_e32 v0, 2, v141
	global_load_lds_dwordx4 v176, s[8:9]
	s_and_b64 s[8:9], s[28:29], exec
	s_cselect_b32 s10, s80, s78
	s_cselect_b32 s11, s79, s27
	s_and_b64 s[8:9], s[66:67], exec
	s_cselect_b32 s56, s16, s11
	s_cselect_b32 s10, s17, s10
	s_and_b64 s[8:9], s[50:51], exec
	s_cselect_b32 s11, s78, s10
	s_cselect_b32 s10, s27, s56
	s_add_i32 s8, s33, 0
	s_add_i32 m0, s8, s77
	v_lshrrev_b32_e32 v2, 1, v141
	global_load_lds_dwordx4 v148, s[10:11]
	s_and_b64 s[10:11], s[60:61], exec
	s_cselect_b32 s9, s80, s78
	s_cselect_b32 s56, s79, s27
	s_and_b64 s[10:11], s[38:39], exec
	s_cselect_b32 s56, s16, s56
	s_cselect_b32 s9, s17, s9
	s_and_b64 s[10:11], s[62:63], exec
	s_cselect_b32 s11, s78, s9
	s_cselect_b32 s10, s27, s56
	s_add_i32 s9, s93, 0
	s_add_i32 m0, s9, s57
	v_and_b32_e32 v1, 3, v141
	global_load_lds_dwordx4 v150, s[10:11]
	s_and_b64 s[10:11], s[6:7], exec
	s_cselect_b32 s56, s80, s78
	s_cselect_b32 s57, s79, s27
	s_and_b64 s[10:11], s[12:13], exec
	s_cselect_b32 s77, s16, s57
	s_cselect_b32 s56, s17, s56
	s_and_b64 s[10:11], s[22:23], exec
	s_cselect_b32 s57, s78, s56
	s_cselect_b32 s56, s27, s77
	s_add_i32 s10, s45, 0
	s_add_i32 m0, s10, s76
	v_and_b32_e32 v2, 12, v2
	global_load_lds_dwordx4 v152, s[56:57]
	s_and_b64 s[56:57], s[14:15], exec
	s_cselect_b32 s11, s80, s78
	s_cselect_b32 s76, s79, s27
	s_and_b64 s[56:57], s[0:1], exec
	s_cselect_b32 s16, s16, s76
	s_cselect_b32 s11, s17, s11
	s_and_b64 s[56:57], s[68:69], exec
	s_cselect_b32 s57, s78, s11
	s_cselect_b32 s56, s27, s16
	s_add_i32 s11, s59, 0
	s_add_i32 m0, s11, s58
	s_or_b32 s27, s88, s5
	global_load_lds_dwordx4 v154, s[56:57]
	s_waitcnt vmcnt(0)
	v_and_b32_e32 v0, 16, v0
	v_or3_b32 v0, v0, v1, v2
	s_cmpk_lt_u32 s4, 0x100
	v_mov_b32_e32 v149, v177
	v_mov_b32_e32 v151, v177
	v_mov_b32_e32 v153, v177
	v_mov_b32_e32 v155, v177
	v_or_b32_e32 v161, s27, v140
	s_cselect_b64 s[76:77], -1, 0
	s_cmpk_gt_u32 s4, 0xff
	s_mov_b64 s[4:5], -1
	v_mul_u32_u24_e32 v162, 0x90, v0
	s_waitcnt vmcnt(0) lgkmcnt(0)
	s_barrier
	s_cbranch_scc0 .LBB0_695
	s_mul_i32 s94, s83, 0x2400
	s_add_i32 s4, s94, 0
	s_waitcnt lgkmcnt(0)
	s_barrier
	v_add3_u32 v2, s4, v162, v146
	ds_read_b128 v[32:35], v2
	ds_read_b128 v[36:39], v2 offset:32
	ds_read_b128 v[40:43], v2 offset:4608
	ds_read_b128 v[44:47], v2 offset:4640
	v_writelane_b32 v255, s76, 31
	s_nop 1
	v_writelane_b32 v255, s77, 32
	s_add_u32 s16, s21, 0xc0000
	s_addc_u32 s17, s84, 0
	s_add_u32 s56, s44, 0x100
	s_addc_u32 s57, s85, 0
	s_add_u32 s58, s21, 0xc0080
	s_addc_u32 s76, s84, 0
	s_and_b64 s[4:5], s[52:53], exec
	s_cselect_b32 s77, s57, s17
	s_cselect_b32 s78, s56, s16
	s_and_b64 s[4:5], s[48:49], exec
	s_cselect_b32 s78, s58, s78
	s_cselect_b32 s77, s76, s77
	s_and_b64 s[4:5], s[36:37], exec
	s_cselect_b32 s5, s17, s77
	s_cselect_b32 s4, s16, s78
	s_add_i32 m0, s26, 0x12000
	v_lshl_add_u64 v[0:1], s[4:5], 0, v[176:177]
	s_and_b64 s[4:5], s[28:29], exec
	s_cselect_b32 s77, s57, s17
	s_cselect_b32 s78, s56, s16
	s_and_b64 s[4:5], s[66:67], exec
	s_cselect_b32 s78, s58, s78
	s_cselect_b32 s77, s76, s77
	s_and_b64 s[4:5], s[50:51], exec
	global_load_lds_dwordx4 v[0:1], off
	s_cselect_b32 s5, s17, s77
	s_cselect_b32 s4, s16, s78
	s_add_i32 m0, s8, 0x12000
	v_lshl_add_u64 v[0:1], s[4:5], 0, v[148:149]
	s_and_b64 s[4:5], s[60:61], exec
	s_cselect_b32 s8, s57, s17
	s_cselect_b32 s77, s56, s16
	s_and_b64 s[4:5], s[38:39], exec
	s_cselect_b32 s77, s58, s77
	s_cselect_b32 s8, s76, s8
	s_and_b64 s[4:5], s[62:63], exec
	global_load_lds_dwordx4 v[0:1], off
	s_cselect_b32 s5, s17, s8
	s_cselect_b32 s4, s16, s77
	s_add_i32 m0, s9, 0x12000
	v_lshl_add_u64 v[0:1], s[4:5], 0, v[150:151]
	s_and_b64 s[4:5], s[6:7], exec
	s_cselect_b32 s8, s57, s17
	s_cselect_b32 s9, s56, s16
	s_and_b64 s[4:5], s[12:13], exec
	s_cselect_b32 s9, s58, s9
	s_cselect_b32 s8, s76, s8
	s_and_b64 s[4:5], s[22:23], exec
	global_load_lds_dwordx4 v[0:1], off
	s_cselect_b32 s5, s17, s8
	s_cselect_b32 s4, s16, s9
	s_add_i32 m0, s10, 0x12000
	v_lshl_add_u64 v[0:1], s[4:5], 0, v[152:153]
	s_and_b64 s[4:5], s[14:15], exec
	s_cselect_b32 s8, s57, s17
	s_cselect_b32 s9, s56, s16
	s_and_b64 s[4:5], s[0:1], exec
	s_cselect_b32 s9, s58, s9
	s_cselect_b32 s8, s76, s8
	s_and_b64 s[4:5], s[68:69], exec
	s_cselect_b32 s5, s17, s8
	s_cselect_b32 s4, s16, s9
	global_load_lds_dwordx4 v[0:1], off
	v_lshl_add_u64 v[0:1], s[4:5], 0, v[154:155]
	s_add_i32 m0, s11, 0x12000
	s_nop 0
	global_load_lds_dwordx4 v[0:1], off
	ds_read_b128 v[48:51], v2 offset:64
	ds_read_b128 v[52:55], v2 offset:96
	ds_read_b128 v[56:59], v2 offset:4672
	ds_read_b128 v[60:63], v2 offset:4704
	s_cmpk_gt_u32 s27, 0xbe
	s_cselect_b64 vcc, -1, 0
	v_cndmask_b32_e32 v142, 0, v159, vcc
	s_mov_b32 s4, 0x7149f2ca
	v_cmp_neq_f32_e64 s[4:5], s4, v142
	s_and_b64 vcc, exec, vcc
	s_nop 0
	v_cndmask_b32_e64 v0, 0, v142, s[4:5]
	v_mov_b32_e32 v1, v0
	v_mov_b32_e32 v2, v0
	v_mov_b32_e32 v3, v0
	v_mov_b32_e32 v4, v0
	v_mov_b32_e32 v5, v0
	v_mov_b32_e32 v6, v0
	v_mov_b32_e32 v7, v0
	v_mov_b32_e32 v8, v0
	v_mov_b32_e32 v9, v0
	v_mov_b32_e32 v10, v0
	v_mov_b32_e32 v11, v0
	v_mov_b32_e32 v12, v0
	v_mov_b32_e32 v13, v0
	v_mov_b32_e32 v14, v0
	v_mov_b32_e32 v15, v0
	s_waitcnt lgkmcnt(0)
	s_nop 0
	v_mfma_f32_32x32x16_bf16 v[16:31], v[32:35], v[112:115], v[0:15]
	v_mfma_f32_32x32x16_bf16 v[0:15], v[40:43], v[112:115], v[0:15]
	v_mfma_f32_32x32x16_bf16 v[16:31], v[36:39], v[116:119], v[16:31]
	v_mfma_f32_32x32x16_bf16 v[0:15], v[44:47], v[116:119], v[0:15]
	v_mfma_f32_32x32x16_bf16 v[16:31], v[48:51], v[120:123], v[16:31]
	v_mfma_f32_32x32x16_bf16 v[0:15], v[56:59], v[120:123], v[0:15]
	v_mfma_f32_32x32x16_bf16 v[16:31], v[52:55], v[124:127], v[16:31]
	v_mfma_f32_32x32x16_bf16 v[0:15], v[60:63], v[124:127], v[0:15]
	s_cbranch_vccnz .LBB0_682
	v_sub_u32_e32 v56, v146, v161
	s_add_i32 s4, 0, 0x20180
	v_max_i32_e32 v34, 0xffffff7f, v56
	v_lshl_add_u32 v36, v34, 2, s4
	v_max_i32_e32 v34, 0xffffff7e, v56
	v_max_i32_e32 v32, 0xffffff80, v56
	v_max_i32_e32 v33, 0xffffff60, v56
	v_max_i32_e32 v35, 0xffffff5f, v56
	v_max_i32_e32 v37, 0xffffff5e, v56
	v_lshl_add_u32 v38, v34, 2, s4
	v_max_i32_e32 v34, 0xffffff7d, v56
	v_max_i32_e32 v39, 0xffffff5d, v56
	v_max_i32_e32 v42, 0xffffff7b, v56
	v_lshl_add_u32 v32, v32, 2, s4
	v_lshl_add_u32 v33, v33, 2, s4
	v_lshl_add_u32 v35, v35, 2, s4
	v_lshl_add_u32 v37, v37, 2, s4
	v_lshl_add_u32 v40, v34, 2, s4
	v_lshl_add_u32 v39, v39, 2, s4
	v_lshl_add_u32 v44, v42, 2, s4
	v_max_i32_e32 v42, 0xffffff7a, v56
	ds_read_b32 v32, v32 offset:512
	ds_read_b32 v34, v33 offset:640
	ds_read_b32 v33, v36 offset:516
	ds_read_b32 v35, v35 offset:644
	ds_read_b32 v36, v38 offset:520
	ds_read_b32 v38, v37 offset:648
	ds_read_b32 v37, v40 offset:524
	ds_read_b32 v39, v39 offset:652
	v_max_i32_e32 v40, 0xffffff7c, v56
	v_max_i32_e32 v41, 0xffffff5c, v56
	v_max_i32_e32 v43, 0xffffff5b, v56
	v_max_i32_e32 v45, 0xffffff5a, v56
	v_lshl_add_u32 v46, v42, 2, s4
	v_max_i32_e32 v42, 0xffffff79, v56
	v_max_i32_e32 v47, 0xffffff59, v56
	v_max_i32_e32 v50, 0xffffff77, v56
	v_lshl_add_u32 v40, v40, 2, s4
	v_lshl_add_u32 v41, v41, 2, s4
	v_lshl_add_u32 v43, v43, 2, s4
	v_lshl_add_u32 v45, v45, 2, s4
	v_lshl_add_u32 v48, v42, 2, s4
	v_lshl_add_u32 v47, v47, 2, s4
	v_lshl_add_u32 v52, v50, 2, s4
	v_max_i32_e32 v50, 0xffffff76, v56
	ds_read_b32 v40, v40 offset:528
	ds_read_b32 v42, v41 offset:656
	ds_read_b32 v41, v44 offset:532
	ds_read_b32 v43, v43 offset:660
	ds_read_b32 v44, v46 offset:536
	ds_read_b32 v46, v45 offset:664
	ds_read_b32 v45, v48 offset:540
	ds_read_b32 v47, v47 offset:668
	v_max_i32_e32 v48, 0xffffff78, v56
	v_max_i32_e32 v49, 0xffffff58, v56
	v_max_i32_e32 v51, 0xffffff57, v56
	v_max_i32_e32 v53, 0xffffff56, v56
	v_lshl_add_u32 v54, v50, 2, s4
	v_max_i32_e32 v50, 0xffffff75, v56
	v_max_i32_e32 v55, 0xffffff55, v56
	v_lshl_add_u32 v48, v48, 2, s4
	v_lshl_add_u32 v49, v49, 2, s4
	v_lshl_add_u32 v51, v51, 2, s4
	v_lshl_add_u32 v53, v53, 2, s4
	v_lshl_add_u32 v57, v50, 2, s4
	v_lshl_add_u32 v55, v55, 2, s4
	v_max_i32_e32 v60, 0xffffff53, v56
	v_max_i32_e32 v61, 0xffffff52, v56
	ds_read_b32 v48, v48 offset:544
	ds_read_b32 v50, v49 offset:672
	ds_read_b32 v49, v52 offset:548
	ds_read_b32 v51, v51 offset:676
	ds_read_b32 v52, v54 offset:552
	ds_read_b32 v54, v53 offset:680
	ds_read_b32 v53, v57 offset:556
	ds_read_b32 v55, v55 offset:684
	v_max_i32_e32 v57, 0xffffff74, v56
	v_max_i32_e32 v58, 0xffffff54, v56
	v_max_i32_e32 v59, 0xffffff73, v56
	v_lshl_add_u32 v64, v60, 2, s4
	v_max_i32_e32 v60, 0xffffff72, v56
	v_lshl_add_u32 v62, v61, 2, s4
	v_max_i32_e32 v61, 0xffffff71, v56
	v_max_i32_e32 v56, 0xffffff51, v56
	v_lshl_add_u32 v57, v57, 2, s4
	v_lshl_add_u32 v58, v58, 2, s4
	v_lshl_add_u32 v59, v59, 2, s4
	v_lshl_add_u32 v60, v60, 2, s4
	v_lshl_add_u32 v61, v61, 2, s4
	v_lshl_add_u32 v63, v56, 2, s4
	ds_read_b32 v56, v57 offset:560
	ds_read_b32 v58, v58 offset:688
	ds_read_b32 v60, v60 offset:568
	ds_read_b32 v61, v61 offset:572
	ds_read_b32 v57, v59 offset:564
	ds_read_b32 v63, v63 offset:700
	ds_read_b32 v62, v62 offset:696
	ds_read_b32 v59, v64 offset:692
	s_waitcnt lgkmcnt(0)
	v_pk_add_f32 v[30:31], v[30:31], v[60:61]
	v_pk_add_f32 v[28:29], v[28:29], v[56:57]
	v_pk_add_f32 v[26:27], v[26:27], v[52:53]
	v_pk_add_f32 v[24:25], v[24:25], v[48:49]
	v_pk_add_f32 v[22:23], v[22:23], v[44:45]
	v_pk_add_f32 v[20:21], v[20:21], v[40:41]
	v_pk_add_f32 v[18:19], v[18:19], v[36:37]
	v_pk_add_f32 v[16:17], v[16:17], v[32:33]
	v_pk_add_f32 v[14:15], v[14:15], v[62:63]
	v_pk_add_f32 v[12:13], v[12:13], v[58:59]
	v_pk_add_f32 v[10:11], v[10:11], v[54:55]
	v_pk_add_f32 v[8:9], v[8:9], v[50:51]
	v_pk_add_f32 v[6:7], v[6:7], v[46:47]
	v_pk_add_f32 v[4:5], v[4:5], v[42:43]
	v_pk_add_f32 v[2:3], v[2:3], v[38:39]
	v_pk_add_f32 v[0:1], v[0:1], v[34:35]

.Lattn_negm_keep_2:
	s_addk_i32 s16, 0xffa1
	s_cmp_lt_u32 s16, 0xfffffea3
	s_nop 0
	s_waitcnt lgkmcnt(7)
	v_mfma_f32_32x32x16_bf16 v[96:111], v[80:83], v[112:115], v[64:79]
	s_waitcnt lgkmcnt(5)
	v_mfma_f32_32x32x16_bf16 v[80:95], v[136:139], v[112:115], v[64:79]
	v_mfma_f32_32x32x16_bf16 v[96:111], v[128:131], v[116:119], v[96:111]
	s_waitcnt lgkmcnt(4)
	v_mfma_f32_32x32x16_bf16 v[80:95], v[132:135], v[116:119], v[80:95]
	s_waitcnt lgkmcnt(3)
	v_mfma_f32_32x32x16_bf16 v[96:111], v[166:169], v[120:123], v[96:111]
	s_waitcnt lgkmcnt(1)
	v_mfma_f32_32x32x16_bf16 v[80:95], v[178:181], v[120:123], v[80:95]
	v_mfma_f32_32x32x16_bf16 v[96:111], v[170:173], v[124:127], v[96:111]
	s_waitcnt lgkmcnt(0)
	v_mfma_f32_32x32x16_bf16 v[80:95], v[182:185], v[124:127], v[80:95]
	s_cbranch_scc1 .LBB0_688
	v_add_u32_e32 v180, s58, v164
	s_mov_b32 s80, 0x20380
	v_lshl_add_u32 v250, v180, 2, s80
	ds_read2_b32 v[128:129], v250 offset0:0 offset1:1
	ds_read2_b32 v[132:133], v250 offset0:2 offset1:3
	ds_read2_b32 v[136:137], v250 offset0:4 offset1:5
	ds_read2_b32 v[166:167], v250 offset0:6 offset1:7
	ds_read2_b32 v[170:171], v250 offset0:8 offset1:9
	ds_read2_b32 v[174:175], v250 offset0:10 offset1:11
	ds_read2_b32 v[180:181], v250 offset0:12 offset1:13
	ds_read2_b32 v[184:185], v250 offset0:14 offset1:15
	ds_read2_b32 v[130:131], v250 offset0:32 offset1:33
	ds_read2_b32 v[134:135], v250 offset0:34 offset1:35
	ds_read2_b32 v[138:139], v250 offset0:36 offset1:37
	ds_read2_b32 v[168:169], v250 offset0:38 offset1:39
	ds_read2_b32 v[172:173], v250 offset0:40 offset1:41
	ds_read2_b32 v[178:179], v250 offset0:42 offset1:43
	ds_read2_b32 v[182:183], v250 offset0:44 offset1:45
	ds_read2_b32 v[186:187], v250 offset0:46 offset1:47
	s_waitcnt lgkmcnt(0)
	v_pk_add_f32 v[110:111], v[110:111], v[184:185]
	v_pk_add_f32 v[108:109], v[108:109], v[180:181]
	v_pk_add_f32 v[106:107], v[106:107], v[174:175]
	v_pk_add_f32 v[104:105], v[104:105], v[170:171]
	v_pk_add_f32 v[102:103], v[102:103], v[166:167]
	v_pk_add_f32 v[100:101], v[100:101], v[136:137]
	v_pk_add_f32 v[98:99], v[98:99], v[132:133]
	v_pk_add_f32 v[96:97], v[96:97], v[128:129]
	v_pk_add_f32 v[94:95], v[94:95], v[186:187]
	v_pk_add_f32 v[92:93], v[92:93], v[182:183]
	v_pk_add_f32 v[90:91], v[90:91], v[178:179]
	v_pk_add_f32 v[88:89], v[88:89], v[172:173]
	v_pk_add_f32 v[86:87], v[86:87], v[168:169]
	v_pk_add_f32 v[84:85], v[84:85], v[138:139]
	v_pk_add_f32 v[82:83], v[82:83], v[134:135]
	v_pk_add_f32 v[80:81], v[80:81], v[130:131]

.LBB0_695:
	s_and_b64 vcc, exec, s[4:5]
	s_mov_b32 s92, 0x12000
	s_mov_b32 s93, 0x14000
	s_mov_b32 s97, 0x16000
	s_movk_i32 s68, 0x4000
	s_movk_i32 s69, 0x6000
	s_mov_b32 s70, 0xc000
	s_mov_b32 s71, 0x18000
	s_mov_b32 s66, 0x8000
	s_mov_b32 s67, 0x1c000
	s_mov_b32 s65, 0x1e000
	s_cbranch_vccz .LBB0_711
	v_add3_u32 v0, 0, v162, v146
	ds_read_b128 v[32:35], v0
	ds_read_b128 v[36:39], v0 offset:32
	ds_read_b128 v[40:43], v0 offset:4608
	ds_read_b128 v[44:47], v0 offset:4640
	ds_read_b128 v[48:51], v0 offset:64
	ds_read_b128 v[52:55], v0 offset:96
	ds_read_b128 v[56:59], v0 offset:4672
	ds_read_b128 v[60:63], v0 offset:4704
	s_cmpk_gt_u32 s27, 0xbe
	s_cselect_b64 vcc, -1, 0
	v_cndmask_b32_e32 v163, 0, v159, vcc
	s_mov_b32 s0, 0x7149f2ca
	v_cmp_neq_f32_e64 s[4:5], s0, v163
	s_and_b64 vcc, exec, vcc
	s_nop 0
	v_cndmask_b32_e64 v0, 0, v163, s[4:5]
	v_mov_b32_e32 v1, v0
	v_mov_b32_e32 v2, v0
	v_mov_b32_e32 v3, v0
	v_mov_b32_e32 v4, v0
	v_mov_b32_e32 v5, v0
	v_mov_b32_e32 v6, v0
	v_mov_b32_e32 v7, v0
	v_mov_b32_e32 v8, v0
	v_mov_b32_e32 v9, v0
	v_mov_b32_e32 v10, v0
	v_mov_b32_e32 v11, v0
	v_mov_b32_e32 v12, v0
	v_mov_b32_e32 v13, v0
	v_mov_b32_e32 v14, v0
	v_mov_b32_e32 v15, v0
	s_waitcnt lgkmcnt(0)
	s_nop 0
	v_mfma_f32_32x32x16_bf16 v[16:31], v[32:35], v[112:115], v[0:15]
	v_mfma_f32_32x32x16_bf16 v[0:15], v[40:43], v[112:115], v[0:15]
	v_mfma_f32_32x32x16_bf16 v[16:31], v[36:39], v[116:119], v[16:31]
	v_mfma_f32_32x32x16_bf16 v[0:15], v[44:47], v[116:119], v[0:15]
	v_mfma_f32_32x32x16_bf16 v[16:31], v[48:51], v[120:123], v[16:31]
	v_mfma_f32_32x32x16_bf16 v[0:15], v[56:59], v[120:123], v[0:15]
	v_mfma_f32_32x32x16_bf16 v[16:31], v[52:55], v[124:127], v[16:31]
	v_mfma_f32_32x32x16_bf16 v[0:15], v[60:63], v[124:127], v[0:15]
	s_cbranch_vccnz .LBB0_698
	v_sub_u32_e32 v56, v146, v161
	s_add_i32 s0, 0, 0x20180
	v_max_i32_e32 v34, 0xffffff7f, v56
	v_lshl_add_u32 v36, v34, 2, s0
	v_max_i32_e32 v34, 0xffffff7e, v56
	v_max_i32_e32 v32, 0xffffff80, v56
	v_max_i32_e32 v33, 0xffffff60, v56
	v_max_i32_e32 v35, 0xffffff5f, v56
	v_max_i32_e32 v37, 0xffffff5e, v56
	v_lshl_add_u32 v38, v34, 2, s0
	v_max_i32_e32 v34, 0xffffff7d, v56
	v_max_i32_e32 v39, 0xffffff5d, v56
	v_max_i32_e32 v42, 0xffffff7b, v56
	v_lshl_add_u32 v32, v32, 2, s0
	v_lshl_add_u32 v33, v33, 2, s0
	v_lshl_add_u32 v35, v35, 2, s0
	v_lshl_add_u32 v37, v37, 2, s0
	v_lshl_add_u32 v40, v34, 2, s0
	v_lshl_add_u32 v39, v39, 2, s0
	v_lshl_add_u32 v44, v42, 2, s0
	v_max_i32_e32 v42, 0xffffff7a, v56
	ds_read_b32 v32, v32 offset:512
	ds_read_b32 v34, v33 offset:640
	ds_read_b32 v33, v36 offset:516
	ds_read_b32 v35, v35 offset:644
	ds_read_b32 v36, v38 offset:520
	ds_read_b32 v38, v37 offset:648
	ds_read_b32 v37, v40 offset:524
	ds_read_b32 v39, v39 offset:652
	v_max_i32_e32 v40, 0xffffff7c, v56
	v_max_i32_e32 v41, 0xffffff5c, v56
	v_max_i32_e32 v43, 0xffffff5b, v56
	v_max_i32_e32 v45, 0xffffff5a, v56
	v_lshl_add_u32 v46, v42, 2, s0
	v_max_i32_e32 v42, 0xffffff79, v56
	v_max_i32_e32 v47, 0xffffff59, v56
	v_max_i32_e32 v50, 0xffffff77, v56
	v_lshl_add_u32 v40, v40, 2, s0
	v_lshl_add_u32 v41, v41, 2, s0
	v_lshl_add_u32 v43, v43, 2, s0
	v_lshl_add_u32 v45, v45, 2, s0
	v_lshl_add_u32 v48, v42, 2, s0
	v_lshl_add_u32 v47, v47, 2, s0
	v_lshl_add_u32 v52, v50, 2, s0
	v_max_i32_e32 v50, 0xffffff76, v56
	ds_read_b32 v40, v40 offset:528
	ds_read_b32 v42, v41 offset:656
	ds_read_b32 v41, v44 offset:532
	ds_read_b32 v43, v43 offset:660
	ds_read_b32 v44, v46 offset:536
	ds_read_b32 v46, v45 offset:664
	ds_read_b32 v45, v48 offset:540
	ds_read_b32 v47, v47 offset:668
	v_max_i32_e32 v48, 0xffffff78, v56
	v_max_i32_e32 v49, 0xffffff58, v56
	v_max_i32_e32 v51, 0xffffff57, v56
	v_max_i32_e32 v53, 0xffffff56, v56
	v_lshl_add_u32 v54, v50, 2, s0
	v_max_i32_e32 v50, 0xffffff75, v56
	v_max_i32_e32 v55, 0xffffff55, v56
	v_lshl_add_u32 v48, v48, 2, s0
	v_lshl_add_u32 v49, v49, 2, s0
	v_lshl_add_u32 v51, v51, 2, s0
	v_lshl_add_u32 v53, v53, 2, s0
	v_lshl_add_u32 v57, v50, 2, s0
	v_lshl_add_u32 v55, v55, 2, s0
	v_max_i32_e32 v60, 0xffffff53, v56
	v_max_i32_e32 v61, 0xffffff52, v56
	ds_read_b32 v48, v48 offset:544
	ds_read_b32 v50, v49 offset:672
	ds_read_b32 v49, v52 offset:548
	ds_read_b32 v51, v51 offset:676
	ds_read_b32 v52, v54 offset:552
	ds_read_b32 v54, v53 offset:680
	ds_read_b32 v53, v57 offset:556
	ds_read_b32 v55, v55 offset:684
	v_max_i32_e32 v57, 0xffffff74, v56
	v_max_i32_e32 v58, 0xffffff54, v56
	v_max_i32_e32 v59, 0xffffff73, v56
	v_lshl_add_u32 v64, v60, 2, s0
	v_max_i32_e32 v60, 0xffffff72, v56
	v_lshl_add_u32 v62, v61, 2, s0
	v_max_i32_e32 v61, 0xffffff71, v56
	v_max_i32_e32 v56, 0xffffff51, v56
	v_lshl_add_u32 v57, v57, 2, s0
	v_lshl_add_u32 v58, v58, 2, s0
	v_lshl_add_u32 v59, v59, 2, s0
	v_lshl_add_u32 v60, v60, 2, s0
	v_lshl_add_u32 v61, v61, 2, s0
	v_lshl_add_u32 v63, v56, 2, s0
	ds_read_b32 v56, v57 offset:560
	ds_read_b32 v58, v58 offset:688
	ds_read_b32 v60, v60 offset:568
	ds_read_b32 v61, v61 offset:572
	ds_read_b32 v57, v59 offset:564
	ds_read_b32 v63, v63 offset:700
	ds_read_b32 v62, v62 offset:696
	ds_read_b32 v59, v64 offset:692
	s_waitcnt lgkmcnt(0)
	v_pk_add_f32 v[30:31], v[30:31], v[60:61]
	v_pk_add_f32 v[28:29], v[28:29], v[56:57]
	v_pk_add_f32 v[26:27], v[26:27], v[52:53]
	v_pk_add_f32 v[24:25], v[24:25], v[48:49]
	v_pk_add_f32 v[22:23], v[22:23], v[44:45]
	v_pk_add_f32 v[20:21], v[20:21], v[40:41]
	v_pk_add_f32 v[18:19], v[18:19], v[36:37]
	v_pk_add_f32 v[16:17], v[16:17], v[32:33]
	v_pk_add_f32 v[14:15], v[14:15], v[62:63]
	v_pk_add_f32 v[12:13], v[12:13], v[58:59]
	v_pk_add_f32 v[10:11], v[10:11], v[54:55]
	v_pk_add_f32 v[8:9], v[8:9], v[50:51]
	v_pk_add_f32 v[6:7], v[6:7], v[46:47]
	v_pk_add_f32 v[4:5], v[4:5], v[42:43]
	v_pk_add_f32 v[2:3], v[2:3], v[38:39]
	v_pk_add_f32 v[0:1], v[0:1], v[34:35]

.Lattn_negm_keep_3:
	s_addk_i32 s16, 0xffa1
	s_cmp_lt_u32 s16, 0xfffffea3
	s_nop 0
	s_waitcnt lgkmcnt(7)
	v_mfma_f32_32x32x16_bf16 v[96:111], v[80:83], v[112:115], v[64:79]
	s_waitcnt lgkmcnt(5)
	v_mfma_f32_32x32x16_bf16 v[80:95], v[132:135], v[112:115], v[64:79]
	v_mfma_f32_32x32x16_bf16 v[96:111], v[128:131], v[116:119], v[96:111]
	s_waitcnt lgkmcnt(4)
	v_mfma_f32_32x32x16_bf16 v[80:95], v[136:139], v[116:119], v[80:95]
	s_waitcnt lgkmcnt(3)
	v_mfma_f32_32x32x16_bf16 v[96:111], v[140:143], v[120:123], v[96:111]
	s_waitcnt lgkmcnt(1)
	v_mfma_f32_32x32x16_bf16 v[80:95], v[172:175], v[120:123], v[80:95]
	v_mfma_f32_32x32x16_bf16 v[96:111], v[168:171], v[124:127], v[96:111]
	s_waitcnt lgkmcnt(0)
	v_mfma_f32_32x32x16_bf16 v[80:95], v[178:181], v[124:127], v[80:95]
	s_cbranch_scc1 .LBB0_702
	v_add_u32_e32 v178, s20, v166
	s_mov_b32 s57, 0x20380
	v_lshl_add_u32 v250, v178, 2, s57
	ds_read2_b32 v[128:129], v250 offset0:0 offset1:1
	ds_read2_b32 v[132:133], v250 offset0:2 offset1:3
	ds_read2_b32 v[136:137], v250 offset0:4 offset1:5
	ds_read2_b32 v[140:141], v250 offset0:6 offset1:7
	ds_read2_b32 v[168:169], v250 offset0:8 offset1:9
	ds_read2_b32 v[172:173], v250 offset0:10 offset1:11
	ds_read2_b32 v[178:179], v250 offset0:12 offset1:13
	ds_read2_b32 v[182:183], v250 offset0:14 offset1:15
	ds_read2_b32 v[130:131], v250 offset0:32 offset1:33
	ds_read2_b32 v[134:135], v250 offset0:34 offset1:35
	ds_read2_b32 v[138:139], v250 offset0:36 offset1:37
	ds_read2_b32 v[142:143], v250 offset0:38 offset1:39
	ds_read2_b32 v[170:171], v250 offset0:40 offset1:41
	ds_read2_b32 v[174:175], v250 offset0:42 offset1:43
	ds_read2_b32 v[180:181], v250 offset0:44 offset1:45
	ds_read2_b32 v[184:185], v250 offset0:46 offset1:47
	s_waitcnt lgkmcnt(0)
	v_pk_add_f32 v[110:111], v[110:111], v[182:183]
	v_pk_add_f32 v[108:109], v[108:109], v[178:179]
	v_pk_add_f32 v[106:107], v[106:107], v[172:173]
	v_pk_add_f32 v[104:105], v[104:105], v[168:169]
	v_pk_add_f32 v[102:103], v[102:103], v[140:141]
	v_pk_add_f32 v[100:101], v[100:101], v[136:137]
	v_pk_add_f32 v[98:99], v[98:99], v[132:133]
	v_pk_add_f32 v[96:97], v[96:97], v[128:129]
	v_pk_add_f32 v[94:95], v[94:95], v[184:185]
	v_pk_add_f32 v[92:93], v[92:93], v[180:181]
	v_pk_add_f32 v[90:91], v[90:91], v[174:175]
	v_pk_add_f32 v[88:89], v[88:89], v[170:171]
	v_pk_add_f32 v[86:87], v[86:87], v[142:143]
	v_pk_add_f32 v[84:85], v[84:85], v[138:139]
	v_pk_add_f32 v[82:83], v[82:83], v[134:135]
	v_pk_add_f32 v[80:81], v[80:81], v[130:131]
